# grid barrier: non-leader workgroups poll the top-level generation word directly (one hop fewer)
# baseline (speedup 1.0000x reference)
; #define LAS __attribute__((address_space(3)))
; __device__ __forceinline__ unsigned xb_ld(unsigned* p)              { return __hip_atomic_load(p, __ATOMIC_RELAXED, __HIP_MEMORY_SCOPE_AGENT); }
; __device__ __forceinline__ unsigned xb_add(unsigned* p, unsigned v) { return __hip_atomic_fetch_add(p, v, __ATOMIC_RELAXED, __HIP_MEMORY_SCOPE_AGENT); }
; __device__ __forceinline__ unsigned xb_xcc_id() { return (unsigned)__builtin_amdgcn_s_getreg((3 << 11) | 20) & 0xFu; }
; #define XB_SPIN(cond, bar) do { unsigned _sp = 0; while (cond) { __builtin_amdgcn_s_sleep(1); \
;     if ((++_sp & 255u) == 0u) { if (xb_ld(&(bar)[XB_TMO])) break; if (_sp > XB_SPIN_CAP) { atomicAdd(&(bar)[XB_TMO], 1u); break; } } } } while (0)
; __device__ __forceinline__ void xcd_barrier(unsigned* bar_, volatile LAS unsigned* st_) {
;     asm volatile("s_waitcnt vmcnt(0)" ::: "memory");
;     __syncthreads();
;     if (threadIdx.x == 0) {
;         XcdBarrier b; b.bar = bar_; b.x = xb_xcc_id(); b.st = st_;
;         unsigned* bar = b.bar;
;         __builtin_amdgcn_s_waitcnt(0);
;         unsigned nloc = b.st[0], nx = b.st[1];
;         if (nloc == 0u) { xcd_barrier_complete(bar, b.x, nloc, nx); b.st[0] = nloc; b.st[1] = nx; }
;         const unsigned old = xb_add(&bar[XB_XSUB(b.x)], 1u);
;         const unsigned gen = old / nloc;
;         if (old + 1u == (gen + 1u) * nloc) {
;             __builtin_amdgcn_fence(__ATOMIC_RELEASE, "agent");
;             asm volatile("s_waitcnt vmcnt(0)" ::: "memory");
;             const unsigned og = xb_add(&bar[XB_TOP], 1u);
;             const unsigned tg = og / nx;
;             if (og + 1u == (tg + 1u) * nx) xb_add(&bar[XB_TOPGEN], 1u);
;             else XB_SPIN(xb_ld(&bar[XB_TOPGEN]) == tg, bar);
;             __builtin_amdgcn_fence(__ATOMIC_ACQUIRE, "agent");
;             xb_add(&bar[XB_XGEN(b.x)], 1u);
;             asm volatile("s_waitcnt vmcnt(0)" ::: "memory");
;         } else {
;             XB_SPIN(xb_ld(&bar[XB_XGEN(b.x)]) == gen, bar);
;             __builtin_amdgcn_fence(__ATOMIC_ACQUIRE, "agent");
;             asm volatile("s_waitcnt vmcnt(0)" ::: "memory");
;         }
.LBB0_880:
	s_lshl_b32 s6, s30, 8
	s_add_u32 s6, s86, s6
	s_addc_u32 s7, s87, 0
	v_mov_b32_e32 v1, s6
	v_add_co_u32_e32 v6, vcc, 0x1a401000, v1
	v_mov_b32_e32 v1, s7
	s_nop 0
	v_addc_co_u32_e32 v7, vcc, 0, v1, vcc
	flat_atomic_add v1, v[6:7], v237 offset:1024 sc0
	v_cvt_f32_u32_e32 v3, v4
	v_sub_u32_e32 v5, 0, v4
	s_add_u32 s29, s6, 0x1a400000
	s_addc_u32 s28, s7, 0
	v_rcp_iflag_f32_e32 v3, v3
	s_waitcnt vmcnt(0) lgkmcnt(0)
	v_add_u32_e32 v6, 1, v1
	v_mul_f32_e32 v3, 0x4f7ffffe, v3
	v_cvt_u32_f32_e32 v3, v3
	v_mul_lo_u32 v5, v5, v3
	v_mul_hi_u32 v5, v3, v5
	v_add_u32_e32 v3, v3, v5
	v_mul_hi_u32 v3, v1, v3
	v_mul_lo_u32 v5, v3, v4
	v_sub_u32_e32 v1, v1, v5
	v_add_u32_e32 v7, 1, v3
	v_cmp_ge_u32_e32 vcc, v1, v4
	v_sub_u32_e32 v5, v1, v4
	s_nop 0
	v_cndmask_b32_e32 v3, v3, v7, vcc
	v_cndmask_b32_e32 v1, v1, v5, vcc
	v_add_u32_e32 v5, 1, v3
	v_cmp_ge_u32_e32 vcc, v1, v4
	s_nop 1
	v_cndmask_b32_e32 v1, v3, v5, vcc
	v_mad_u64_u32 v[4:5], s[6:7], v4, v1, v[4:5]
	v_cmp_ne_u32_e32 vcc, v6, v4
	s_and_saveexec_b64 s[6:7], vcc
	s_xor_b64 s[6:7], exec, s[6:7]
	s_cbranch_execz .LBB0_893
	s_add_u32 s10, s86, 0x1a403500
	s_addc_u32 s11, s87, 0
	v_mov_b64_e32 v[2:3], s[10:11]
	global_load_dword v2, v[2:3], off sc1
	s_waitcnt vmcnt(0) lgkmcnt(0)
	v_cmp_eq_u32_e32 vcc, v2, v1
	s_and_saveexec_b64 s[8:9], vcc
	s_cbranch_execz .LBB0_892
	s_add_u32 s12, s86, 0x1a400200
	s_addc_u32 s13, s87, 0
	s_mov_b32 s30, 1
	s_mov_b64 s[14:15], 0
	s_branch .LBB0_884
